# V-image items: a first walk over the wave's item list issues the row loads of all its items (dead registers) before the real walk
# baseline (speedup 1.0000x reference)
; #define LAS __attribute__((address_space(3)))
; __device__ __forceinline__ int hs_dil(int hs) { return (hs >= 14 && hs < 17) ? 4 : ((hs >= 17 && hs < 20) ? 16 : 1); }
; __device__ __forceinline__ void vprep_item(const bf16* PROJ, unsigned char* VTB, int item, LAS unsigned* s32, int lane) {
;     const int kb = item % VTB_KB, hs = (item / VTB_KB) % NHS, b = item / (VTB_KB * NHS);
;     const int dil = hs_dil(hs), col = hs_col(hs), tk = lane & 31, half = lane >> 5;
;     const int pos = kb * 32 + tk, seg = SEQ / dil, token = pos / seg + dil * (pos % seg);
;     const v4u* src = (const v4u*)(PROJ + ((size_t)b * SEQ + token) * NINP + col + 32 * half);
; __device__ __forceinline__ void pre_attn(const bf16* PROJ, const float* fbias, unsigned char* ws, int layer, LAS unsigned char* lds, int bid, int G, int gw, int NGW, int wave, int lane) {
;     ...
;     if (bstride == 4 && G % 4 == 0 && G >= 64) { const bool cum = bid % 4 == 1 && (bid - 1) / 4 < BATCH * 7;
;         if (bid % 4 != 0 && !cum) { int ncum = (bid + 2) / 4; ncum = ncum > BATCH * 7 ? BATCH * 7 : ncum;
;             const int idx = (bid / 4) * 3 + (bid % 4 - 1) - ncum, nw = (G - G / 4 - BATCH * 7) * NWAVES;
;             for (int it = idx * NWAVES + wave; it < BATCH * NHS * VTB_KB; it += nw) vprep_item(PROJ, ws + WS_VTB, it, (LAS unsigned*)(lds + wave * 16384), lane); } }
.LBB0_391:
	s_andn2_b64 vcc, exec, s[2:3]
	s_cbranch_vccnz .LBB0_412
	s_lshr_b32 s2, s26, 30
	s_add_i32 s3, s25, s2
	s_and_b32 s2, s3, -4
	s_sub_i32 s2, s25, s2
	s_cmp_eq_u32 s2, 1
	s_cselect_b64 s[6:7], -1, 0
	s_cmp_lt_i32 s25, 57
	s_cselect_b64 s[8:9], -1, 0
	s_and_b64 s[6:7], s[8:9], s[6:7]
	s_cmp_eq_u32 s2, 0
	s_cselect_b64 s[8:9], -1, 0
	s_or_b64 s[6:7], s[8:9], s[6:7]
	s_and_b64 vcc, exec, s[6:7]
	s_cbranch_vccnz .LBB0_412
	s_add_i32 s4, s25, 2
	s_ashr_i32 s6, s4, 31
	s_lshr_b32 s6, s6, 30
	s_add_i32 s4, s4, s6
	s_ashr_i32 s3, s3, 2
	s_ashr_i32 s4, s4, 2
	s_min_i32 s4, s4, 14
	s_mul_i32 s3, s3, 3
	s_add_i32 s2, s2, s3
	s_not_b32 s3, s4
	s_add_i32 s3, s3, s2
	s_lshl_b32 s2, s3, 3
	s_add_i32 s4, s2, s24
	s_cmpk_gt_i32 s4, 0x1bff
	s_cbranch_scc1 .LBB0_412
	s_lshr_b32 s2, s5, 2
	s_sub_i32 s2, s5, s2
	s_lshl_b32 s5, s2, 3
	s_addk_i32 s5, 0xff90
	s_add_u32 s6, s54, 0x2c800000
	s_addc_u32 s7, s55, 0
	s_lshl_b32 s2, s24, 14
	s_add_i32 s2, s2, 0
	v_and_b32_e32 v8, 31, v1
	v_lshrrev_b32_e32 v4, 5, v58
	v_and_b32_e32 v2, 32, v1
	v_mov_b32_e32 v1, s2
	s_movk_i32 s3, 0x84
	v_mad_u32_u24 v9, v8, s3, v1
	v_lshlrev_b32_e32 v10, 6, v4
	v_lshlrev_b32_e32 v1, 1, v2
	v_lshlrev_b32_e32 v5, 1, v8
	v_add3_u32 v1, s2, v1, v5
	v_lshlrev_b32_e32 v4, 11, v4
	v_mov_b32_e32 v5, v3
	v_lshlrev_b32_e32 v6, 6, v8
	v_mov_b32_e32 v7, v3
	v_lshl_or_b32 v8, s4, 5, v8
	s_lshl_b32 s8, s5, 5
	v_lshlrev_b32_e32 v2, 1, v2
	v_add_u32_e32 v9, v9, v10
	v_mov_b32_e32 v160, v8
	s_mov_b32 s99, s4
	s_branch .Lmy_vp_396
.Lmy_vp_395:
	s_mul_hi_i32 s12, s4, 0x92492493
	s_add_i32 s12, s12, s4
	s_lshr_b32 s13, s12, 31
	s_ashr_i32 s12, s12, 11
	s_add_i32 s16, s12, s13
	s_lshl_b32 s12, s3, 7
	s_sub_i32 s10, s9, 17
	s_add_i32 s11, s9, -14
	s_sub_i32 s14, s4, s12
	s_lshl_b32 s3, s3, 12
	s_cmp_lt_u32 s10, 3
	s_movk_i32 s10, 0x100
	s_cselect_b32 s10, s10, 0x1000
	s_cselect_b32 s12, 4, 0
	s_cmp_lt_u32 s11, 3
	s_cselect_b32 s10, 0x400, s10
	s_cselect_b32 s11, 2, s12
	s_abs_i32 s12, s10
	v_cvt_f32_u32_e32 v10, s12
	v_subrev_u32_e32 v11, s3, v8
	s_sub_i32 s3, 0, s12
	v_sub_u32_e32 v13, 0, v11
	v_rcp_iflag_f32_e32 v10, v10
	v_max_i32_e32 v13, v11, v13
	v_xor_b32_e32 v12, s10, v11
	v_ashrrev_i32_e32 v12, 31, v12
	v_mul_f32_e32 v10, 0x4f7ffffe, v10
	v_cvt_u32_f32_e32 v10, v10
	s_ashr_i32 s17, s16, 31
	s_ashr_i32 s15, s14, 31
	v_add_u32_e32 v8, s8, v8
	v_mul_lo_u32 v14, s3, v10
	v_mul_hi_u32 v14, v10, v14
	v_add_u32_e32 v10, v10, v14
	v_mul_hi_u32 v10, v13, v10
	v_mul_lo_u32 v14, v10, s12
	v_sub_u32_e32 v13, v13, v14
	v_add_u32_e32 v14, 1, v10
	v_cmp_le_u32_e32 vcc, s12, v13
	s_ashr_i32 s3, s2, 31
	s_nop 0
	v_cndmask_b32_e32 v10, v10, v14, vcc
	v_subrev_u32_e32 v14, s12, v13
	v_cndmask_b32_e32 v13, v13, v14, vcc
	v_add_u32_e32 v14, 1, v10
	v_cmp_le_u32_e32 vcc, s12, v13
	s_nop 1
	v_cndmask_b32_e32 v10, v10, v14, vcc
	v_xor_b32_e32 v10, v10, v12
	v_sub_u32_e32 v10, v10, v12
	v_mul_lo_u32 v12, v10, s10
	v_sub_u32_e32 v11, v11, v12
	v_lshl_add_u32 v10, v11, s11, v10
	s_lshl_b64 s[10:11], s[16:17], 12
	v_ashrrev_i32_e32 v11, 31, v10
	v_lshl_add_u64 v[10:11], s[10:11], 0, v[10:11]
	v_mov_b64_e32 v[12:13], s[52:53]
	v_mad_u64_u32 v[12:13], s[10:11], v10, s83, v[12:13]
	v_mad_i32_i24 v13, v11, s83, v13
	v_lshl_add_u64 v[10:11], s[2:3], 1, v[12:13]
	v_lshl_add_u64 v[14:15], v[10:11], 0, v[2:3]
	global_load_dwordx4 v[162:165], v[14:15], off
	global_load_dwordx4 v[166:169], v[14:15], off offset:16
	global_load_dwordx4 v[170:173], v[14:15], off offset:32
	global_load_dwordx4 v[174:177], v[14:15], off offset:48
	s_add_i32 s4, s4, s5
	s_cmpk_gt_i32 s4, 0x1bff
	s_cbranch_scc1 .Lmy_vp_done

; #define LAS __attribute__((address_space(3)))
; __device__ __forceinline__ void pre_attn(const bf16* PROJ, const float* fbias, unsigned char* ws, int layer, LAS unsigned char* lds, int bid, int G, int gw, int NGW, int wave, int lane) {
;     ...
;             for (int it = idx * NWAVES + wave; it < BATCH * NHS * VTB_KB; it += nw) vprep_item(PROJ, ws + WS_VTB, it, (LAS unsigned*)(lds + wave * 16384), lane); } }
.Lmy_vp_done:
	s_mov_b32 s4, s99
	v_mov_b32_e32 v8, v160
	s_branch .LBB0_396
